# static s_setprio 1 for waves 4-7 only inside the two attention phases (reset to 0 before their grid barriers)
# speedup vs baseline: 1.0025x; 1.0000x over previous
.LBB0_685:
	v_readfirstlane_b32 s100, v0
	s_nop 3
	s_and_b32 s100, s100, 0x3ff
	s_lshr_b32 s100, s100, 6
	s_cmp_ge_u32 s100, 4
	s_cbranch_scc0 .Lprio_done_a
	s_setprio 1

.LBB0_921:
	v_readlane_b32 s6, v250, 12
	s_add_i32 s38, s6, 5
	s_cmp_lt_i32 s38, s43
	s_cselect_b64 s[6:7], -1, 0
	s_and_b64 s[6:7], s[8:9], s[6:7]
	v_readlane_b32 s10, v254, 61
	v_readlane_b32 s80, v255, 3
	s_andn2_b64 vcc, exec, s[6:7]
	s_mov_b32 s24, 0x32900000
	v_readlane_b32 s43, v254, 50
	v_readlane_b32 s11, v254, 62
	v_readlane_b32 s81, v255, 4
	s_cbranch_vccnz .LBB0_975
	s_waitcnt vmcnt(0)
	s_waitcnt vmcnt(0) lgkmcnt(0)
	s_setprio 0
	s_barrier
	s_mov_b64 s[6:7], exec
	v_readlane_b32 s8, v251, 7
	v_readlane_b32 s9, v251, 8
	s_and_b64 s[8:9], s[6:7], s[8:9]
	s_mov_b64 exec, s[8:9]
	s_cbranch_execz .LBB0_974
	v_readlane_b32 s8, v254, 33
	s_waitcnt vmcnt(0) expcnt(0) lgkmcnt(0)
	s_nop 0
	v_mov_b32_e32 v1, s8
	ds_read_b32 v4, v1
	v_readlane_b32 s8, v254, 34
	s_waitcnt lgkmcnt(0)
	v_cmp_ne_u32_e32 vcc, 0, v4
	v_mov_b32_e32 v1, s8
	ds_read_b32 v2, v1
	s_cbranch_vccnz .LBB0_938
	v_readlane_b32 s10, v250, 10
	v_readlane_b32 s11, v250, 11
	s_load_dwordx2 s[8:9], s[10:11], 0x4
	s_mov_b32 s15, 1
	s_waitcnt lgkmcnt(0)
	s_mul_i32 s14, s8, s97
	s_mul_i32 s14, s14, s9
	s_branch .LBB0_926

.LBB0_1403:
	v_readlane_b32 s6, v250, 12
	s_add_i32 s38, s6, 4
	s_cmp_lt_i32 s38, s43
	s_cselect_b64 s[6:7], -1, 0
	s_and_b64 s[6:7], s[8:9], s[6:7]
	v_readlane_b32 s10, v254, 61
	s_andn2_b64 vcc, exec, s[6:7]
	s_mov_b32 s24, 0x32900000
	v_readlane_b32 s43, v254, 50
	v_readlane_b32 s11, v254, 62
	s_cbranch_vccnz .LBB0_1457
	s_waitcnt vmcnt(0)
	s_waitcnt vmcnt(0) lgkmcnt(0)
	s_setprio 0
	s_barrier
	s_mov_b64 s[6:7], exec
	v_readlane_b32 s8, v251, 7
	v_readlane_b32 s9, v251, 8
	s_and_b64 s[8:9], s[6:7], s[8:9]
	s_mov_b64 exec, s[8:9]
	s_cbranch_execz .LBB0_1456
	v_readlane_b32 s8, v254, 33
	s_waitcnt vmcnt(0) expcnt(0) lgkmcnt(0)
	s_nop 0
	v_mov_b32_e32 v1, s8
	ds_read_b32 v4, v1
	v_readlane_b32 s8, v254, 34
	s_waitcnt lgkmcnt(0)
	v_cmp_ne_u32_e32 vcc, 0, v4
	v_mov_b32_e32 v1, s8
	ds_read_b32 v2, v1
	s_cbranch_vccnz .LBB0_1420
	v_readlane_b32 s10, v250, 10
	v_readlane_b32 s11, v250, 11
	s_load_dwordx2 s[8:9], s[10:11], 0x4
	s_mov_b32 s15, 1
	s_waitcnt lgkmcnt(0)
	s_mul_i32 s14, s8, s97
	s_mul_i32 s14, s14, s9
	s_branch .LBB0_1408
